# grid barrier: agent acquire (buffer_inv sc1) issued on arrival instead of after release; leader release no longer waited for
# speedup vs baseline: 1.0264x; 1.0264x over previous
.LBB0_11:
	s_or_b64 exec, exec, s[26:27]
	v_add_co_u32_e32 v2, vcc, 0x2000, v4
	s_waitcnt vmcnt(0) lgkmcnt(0)
	v_addc_co_u32_e32 v3, vcc, 0, v5, vcc
	flat_atomic_add v[2:3], v223 offset:1024

.LBB0_860:
	v_readlane_b32 s0, v252, 10
	s_lshl_b32 s50, s0, 2
	v_lshl_add_u64 v[4:5], v[2:3], 0, s[50:51]
	v_add_co_u32_e32 v10, vcc, 0x1000, v4
	v_cvt_f32_u32_e32 v1, v8
	s_nop 0
	v_addc_co_u32_e32 v11, vcc, 0, v5, vcc
	flat_atomic_add v7, v[10:11], v223 offset:1024 sc0
	v_rcp_iflag_f32_e32 v1, v1
	v_sub_u32_e32 v9, 0, v8
	v_mul_f32_e32 v1, 0x4f7ffffe, v1
	v_cvt_u32_f32_e32 v1, v1
	v_mul_lo_u32 v9, v9, v1
	v_mul_hi_u32 v9, v1, v9
	v_add_u32_e32 v1, v1, v9
	s_waitcnt vmcnt(0) lgkmcnt(0)
	v_mul_hi_u32 v1, v7, v1
	v_mul_lo_u32 v9, v1, v8
	v_sub_u32_e32 v9, v7, v9
	v_cmp_ge_u32_e32 vcc, v9, v8
	v_add_u32_e32 v10, 1, v1
	v_add_u32_e32 v7, 1, v7
	v_cndmask_b32_e32 v1, v1, v10, vcc
	v_sub_u32_e32 v10, v9, v8
	v_cndmask_b32_e32 v9, v9, v10, vcc
	v_cmp_ge_u32_e32 vcc, v9, v8
	v_add_u32_e32 v9, 1, v1
	s_nop 0
	v_cndmask_b32_e32 v1, v1, v9, vcc
	v_mad_u64_u32 v[8:9], s[0:1], v8, v1, v[8:9]
	v_cmp_ne_u32_e32 vcc, v7, v8
	s_and_saveexec_b64 s[0:1], vcc
	s_xor_b64 s[26:27], exec, s[0:1]
	s_cbranch_execz .LBB0_873
	v_add_co_u32_e32 v6, vcc, 0x2000, v4
	s_nop 1
	v_addc_co_u32_e32 v7, vcc, 0, v5, vcc
	buffer_inv sc1
	flat_load_dword v6, v[6:7] offset:1024 sc1
	s_waitcnt vmcnt(0) lgkmcnt(0)
	v_cmp_eq_u32_e32 vcc, v6, v1
	s_and_saveexec_b64 s[30:31], vcc
	s_cbranch_execz .LBB0_872
	s_mov_b64 s[0:1], 0x2400
	v_lshl_add_u64 v[4:5], v[4:5], 0, s[0:1]
	s_mov_b32 s0, 1
	s_mov_b64 s[36:37], 0
	s_branch .LBB0_864

.LBB0_872:
	s_or_b64 exec, exec, s[30:31]
	s_waitcnt vmcnt(0) lgkmcnt(0)
	s_waitcnt vmcnt(0)
.LBB0_873:
	s_andn2_saveexec_b64 s[0:1], s[26:27]
	s_cbranch_execz .LBB0_12
	v_add_co_u32_e32 v8, vcc, 0x3000, v2
	buffer_wbl2 sc1
	buffer_inv sc1
	s_waitcnt vmcnt(0)
	s_nop 0
	v_addc_co_u32_e32 v9, vcc, 0, v3, vcc
	flat_atomic_add v7, v[8:9], v223 offset:1024 sc0
	v_cvt_f32_u32_e32 v1, v6
	v_sub_u32_e32 v8, 0, v6
	s_mov_b64 s[30:31], -1
	v_rcp_iflag_f32_e32 v1, v1
	s_nop 0
	v_mul_f32_e32 v1, 0x4f7ffffe, v1
	v_cvt_u32_f32_e32 v1, v1
	v_mul_lo_u32 v8, v8, v1
	v_mul_hi_u32 v8, v1, v8
	v_add_u32_e32 v1, v1, v8
	s_waitcnt vmcnt(0) lgkmcnt(0)
	v_mul_hi_u32 v1, v7, v1
	v_mul_lo_u32 v8, v1, v6
	v_sub_u32_e32 v8, v7, v8
	v_cmp_ge_u32_e32 vcc, v8, v6
	v_add_u32_e32 v9, 1, v1
	s_nop 0
	v_cndmask_b32_e32 v1, v1, v9, vcc
	v_sub_u32_e32 v9, v8, v6
	v_cndmask_b32_e32 v8, v8, v9, vcc
	v_cmp_ge_u32_e32 vcc, v8, v6
	v_add_u32_e32 v8, 1, v1
	s_nop 0
	v_cndmask_b32_e32 v1, v1, v8, vcc
	v_add_u32_e32 v8, 1, v7
	v_mad_u64_u32 v[6:7], s[0:1], v6, v1, v[6:7]
	s_mov_b64 s[0:1], 0x3500
	v_cmp_ne_u32_e32 vcc, v8, v6
	v_lshl_add_u64 v[6:7], v[2:3], 0, s[0:1]
	s_and_saveexec_b64 s[26:27], vcc
	s_cbranch_execz .LBB0_890
	flat_load_dword v8, v[6:7] sc1
	s_mov_b64 s[36:37], 0
	s_waitcnt vmcnt(0) lgkmcnt(0)
	v_cmp_eq_u32_e32 vcc, v8, v1
	s_and_saveexec_b64 s[30:31], vcc
	s_cbranch_execz .LBB0_889
	s_mov_b64 s[0:1], 0x200
	v_lshl_add_u64 v[8:9], v[2:3], 0, s[0:1]
	s_mov_b32 s0, 1
	s_branch .LBB0_878
